# blocked H + attention main-loop edge edit: post-barrier SALU/VALU moved ahead of each step barrier, each step leads with its first QK MFMA
# speedup vs baseline: 1.0027x; 1.0011x over previous
; #define WAIT_BAR(N) asm volatile("s_waitcnt vmcnt(" #N ") lgkmcnt(0)\n\ts_barrier":::"memory")
;   #define RESC() do{ if(resc){ asm volatile("s_waitcnt lgkmcnt(0)":::"memory"); \
;       _Pragma("unroll") for(int d_=0;d_<2;++d_) _Pragma("unroll") for(int r=0;r<16;++r)o[d_][r]*=wsf[crow(r,hi)]; } }while(0)
;   #define ROT() do{sl_prev=sl_cur;sl_cur=sl_next;sl_next=(sl_next==(NSLOT-1)*SLOTB)?0:sl_next+SLOTB;}while(0)
; template<int THRL,bool NOMAX> __device__ __forceinline__ void attn_unit(long rowbase,int NT,int h,int qb,const bf16*Q,const bf16*__restrict__ Kh,const bf16*__restrict__ Vh,bf16*O,char*shm,
;     bool first,bool has_next,long n_rowbase,int n_h,int n_qb,const bf16*__restrict__ n_Kh,bf16x8 (&qr)[4]){
;     ...
;     STEP(pB0,pB1,pA0,pA1,t,true,true,true);     WAIT_BAR(2); RESC(); ROT();
.LBB0_1097:
	s_mov_b32 s7, s89
	s_mov_b32 s88, s38
	s_mov_b32 s37, s87
	v_mfma_f32_32x32x16_bf16 v[114:129], v[190:193], v[130:133], v[50:65]
	v_mov_b64_e32 v[226:227], v[100:101]
	v_mov_b64_e32 v[228:229], v[98:99]
	v_add_u32_e32 v198, s36, v233
	ds_read_b64_tr_b16 v[200:201], v198 offset:24576
	ds_read_b64_tr_b16 v[202:203], v198 offset:25088
	v_add_f32_e32 v98, v82, v83
	v_add_f32_e32 v98, v84, v98
	v_add_f32_e32 v98, v85, v98
	v_add_f32_e32 v98, v86, v98
	v_add_f32_e32 v98, v87, v98
	v_cvt_pk_bf16_f32 v158, v82, v83
	v_cvt_pk_bf16_f32 v159, v84, v85
	s_waitcnt lgkmcnt(9)
	ds_read_b64_tr_b16 v[82:83], v198 offset:28672
	ds_read_b64_tr_b16 v[84:85], v198 offset:29184
	v_add_f32_e32 v98, v88, v98
	v_add_f32_e32 v98, v89, v98
	v_add_f32_e32 v98, v90, v98
	v_add_f32_e32 v146, v91, v98
	s_waitcnt lgkmcnt(10)
	v_mfma_f32_32x32x16_bf16 v[98:113], v[186:189], v[130:133], v[50:65]
	v_cvt_pk_bf16_f32 v160, v86, v87
	v_cvt_pk_bf16_f32 v161, v88, v89
	ds_read_b64_tr_b16 v[86:87], v198 offset:25600
	ds_read_b64_tr_b16 v[88:89], v198 offset:26112
	v_add_f32_e32 v146, v92, v146
	v_add_f32_e32 v146, v93, v146
	v_add_f32_e32 v146, v94, v146
	v_add_f32_e32 v146, v95, v146
	v_cvt_pk_bf16_f32 v154, v90, v91
	v_cvt_pk_bf16_f32 v155, v92, v93
	s_waitcnt lgkmcnt(11)
	v_mfma_f32_32x32x16_bf16 v[114:129], v[182:185], v[134:137], v[114:129]
	ds_read_b64_tr_b16 v[90:91], v198 offset:29696
	ds_read_b64_tr_b16 v[92:93], v198 offset:30208
	s_waitcnt lgkmcnt(12)
	v_mfma_f32_32x32x16_bf16 v[98:113], v[178:181], v[134:137], v[98:113]
	v_add_f32_e32 v146, v96, v146
	v_add_f32_e32 v146, v97, v146
	v_add_f32_e32 v146, v66, v146
	v_add_f32_e32 v146, v67, v146
	v_cvt_pk_bf16_f32 v156, v94, v95
	v_cvt_pk_bf16_f32 v157, v96, v97
	ds_read_b64_tr_b16 v[94:95], v198 offset:26624
	ds_read_b64_tr_b16 v[96:97], v198 offset:27136
	v_add_f32_e32 v146, v68, v146
	v_add_f32_e32 v146, v69, v146
	v_add_f32_e32 v146, v70, v146
	v_add_f32_e32 v146, v71, v146
	v_cvt_pk_bf16_f32 v150, v66, v67
	v_cvt_pk_bf16_f32 v151, v68, v69
	s_waitcnt lgkmcnt(13)
	v_mfma_f32_32x32x16_bf16 v[114:129], v[174:177], v[138:141], v[114:129]
	ds_read_b64_tr_b16 v[66:67], v198 offset:30720
	ds_read_b64_tr_b16 v[68:69], v198 offset:31232
	s_waitcnt lgkmcnt(14)
	v_mfma_f32_32x32x16_bf16 v[98:113], v[170:173], v[138:141], v[98:113]
	v_add_f32_e32 v146, v72, v146
	v_add_f32_e32 v146, v73, v146
	v_add_f32_e32 v146, v74, v146
	v_add_f32_e32 v146, v75, v146
	v_cvt_pk_bf16_f32 v152, v70, v71
	v_cvt_pk_bf16_f32 v153, v72, v73
	ds_read_b64_tr_b16 v[70:71], v198 offset:27648
	ds_read_b64_tr_b16 v[72:73], v198 offset:28160
	v_add_f32_e32 v146, v76, v146
	v_add_f32_e32 v146, v77, v146
	v_add_f32_e32 v146, v78, v146
	v_add_f32_e32 v170, v79, v146
	v_cvt_pk_bf16_f32 v146, v74, v75
	v_cvt_pk_bf16_f32 v147, v76, v77
	s_waitcnt lgkmcnt(14)
	v_mfma_f32_32x32x16_bf16 v[114:129], v[166:169], v[142:145], v[114:129]
	ds_read_b64_tr_b16 v[74:75], v198 offset:31744
	ds_read_b64_tr_b16 v[76:77], v198 offset:32256
	v_mfma_f32_32x32x16_bf16 v[98:113], v[162:165], v[142:145], v[98:113]
	v_add_f32_e32 v148, v80, v170
	v_add_f32_e32 v148, v81, v148
	v_add_f32_e32 v198, 0, v148
	v_cvt_pk_bf16_f32 v148, v78, v79
	v_cvt_pk_bf16_f32 v149, v80, v81
	v_lshl_add_u64 v[78:79], v[196:197], 0, s[24:25]
	s_add_i32 s0, s87, s84
	s_mov_b32 s1, m0
	s_mov_b32 m0, s0
	s_nop 0
	global_load_lds_dwordx4 v[78:79], off
	s_mov_b32 m0, s1
	v_lshl_add_u64 v[78:79], v[194:195], 0, s[24:25]
	s_add_i32 s0, s89, s8
	s_mov_b32 s1, m0
	s_mov_b32 m0, s0
	s_nop 0
	global_load_lds_dwordx4 v[78:79], off
	s_mov_b32 m0, s1
	s_waitcnt lgkmcnt(14)
	v_mfma_f32_32x32x16_bf16 v[18:33], v[158:161], v[200:203], v[18:33]
	v_exp_f32_e32 v114, v114
	v_exp_f32_e32 v115, v115
	v_exp_f32_e32 v116, v116
	v_exp_f32_e32 v117, v117
	s_waitcnt lgkmcnt(12)
	v_mfma_f32_32x32x16_bf16 v[34:49], v[158:161], v[82:85], v[34:49]
	v_exp_f32_e32 v118, v118
	v_exp_f32_e32 v119, v119
	v_exp_f32_e32 v120, v120
	v_exp_f32_e32 v121, v121
	v_add_u32_e32 v82, s7, v232
	ds_read_b128 v[78:81], v82
	ds_read_b128 v[162:165], v82 offset:512
	s_waitcnt lgkmcnt(12)
	v_mfma_f32_32x32x16_bf16 v[18:33], v[154:157], v[86:89], v[18:33]
	v_exp_f32_e32 v122, v122
	v_exp_f32_e32 v123, v123
	v_exp_f32_e32 v124, v124
	v_exp_f32_e32 v125, v125
	ds_read_b128 v[166:169], v82 offset:2048
	ds_read_b128 v[170:173], v82 offset:2560
	s_waitcnt lgkmcnt(12)
	v_mfma_f32_32x32x16_bf16 v[34:49], v[154:157], v[90:93], v[34:49]
	v_exp_f32_e32 v126, v126
	v_exp_f32_e32 v127, v127
	v_exp_f32_e32 v128, v128
	v_exp_f32_e32 v129, v129
	ds_read_b128 v[174:177], v82 offset:4096
	ds_read_b128 v[178:181], v82 offset:4608
	s_waitcnt lgkmcnt(12)
	v_mfma_f32_32x32x16_bf16 v[18:33], v[150:153], v[94:97], v[18:33]
	v_exp_f32_e32 v98, v98
	v_exp_f32_e32 v99, v99
	v_exp_f32_e32 v100, v100
	v_exp_f32_e32 v101, v101
	ds_read_b128 v[182:185], v82 offset:6144
	ds_read_b128 v[186:189], v82 offset:6656
	s_waitcnt lgkmcnt(12)
	v_mfma_f32_32x32x16_bf16 v[34:49], v[150:153], v[66:69], v[34:49]
	v_exp_f32_e32 v102, v102
	v_exp_f32_e32 v103, v103
	v_exp_f32_e32 v104, v104
	v_exp_f32_e32 v105, v105
	s_waitcnt lgkmcnt(10)
	v_mfma_f32_32x32x16_bf16 v[18:33], v[146:149], v[70:73], v[18:33]
	v_exp_f32_e32 v106, v106
	v_exp_f32_e32 v107, v107
	v_exp_f32_e32 v108, v108
	v_exp_f32_e32 v109, v109
	s_waitcnt lgkmcnt(8)
	v_mfma_f32_32x32x16_bf16 v[34:49], v[146:149], v[74:77], v[34:49]
	v_exp_f32_e32 v110, v110
	v_exp_f32_e32 v111, v111
	v_exp_f32_e32 v112, v112
	v_exp_f32_e32 v113, v113
	s_add_i32 s0, s89, 0x2000
	s_cmpk_lg_i32 s89, 0x4000
	s_cselect_b32 s87, s0, 0
	s_waitcnt vmcnt(2) lgkmcnt(0)
	s_barrier
; #define WAIT_BAR(N) asm volatile("s_waitcnt vmcnt(" #N ") lgkmcnt(0)\n\ts_barrier":::"memory")
;   #define RESC() do{ if(resc){ asm volatile("s_waitcnt lgkmcnt(0)":::"memory"); \
;       _Pragma("unroll") for(int d_=0;d_<2;++d_) _Pragma("unroll") for(int r=0;r<16;++r)o[d_][r]*=wsf[crow(r,hi)]; } }while(0)
;   #define ROT() do{sl_prev=sl_cur;sl_cur=sl_next;sl_next=(sl_next==(NSLOT-1)*SLOTB)?0:sl_next+SLOTB;}while(0)
; template<int THRL,bool NOMAX> __device__ __forceinline__ void attn_unit(long rowbase,int NT,int h,int qb,const bf16*Q,const bf16*__restrict__ Kh,const bf16*__restrict__ Vh,bf16*O,char*shm,
;     bool first,bool has_next,long n_rowbase,int n_h,int n_qb,const bf16*__restrict__ n_Kh,bf16x8 (&qr)[4]){
;     ...
;     STEP(pA0,pA1,pB0,pB1,t+1,true,true,true);   WAIT_BAR(2); RESC(); ROT();
;   }
	v_mfma_f32_32x32x16_bf16 v[82:97], v[78:81], v[130:133], v[50:65]
	v_add_u32_e32 v199, s37, v233
	ds_read_b64_tr_b16 v[190:191], v199 offset:24576
	ds_read_b64_tr_b16 v[192:193], v199 offset:25088
	s_waitcnt lgkmcnt(9)
	v_add_f32_e32 v66, v114, v115
	v_add_f32_e32 v66, v116, v66
	v_add_f32_e32 v66, v117, v66
	v_add_f32_e32 v66, v118, v66
	v_add_f32_e32 v66, v119, v66
	v_cvt_pk_bf16_f32 v158, v114, v115
	v_cvt_pk_bf16_f32 v159, v116, v117
	ds_read_b64_tr_b16 v[114:115], v199 offset:28672
	ds_read_b64_tr_b16 v[116:117], v199 offset:29184
	v_add_f32_e32 v66, v120, v66
	v_add_f32_e32 v66, v121, v66
	v_add_f32_e32 v66, v122, v66
	v_add_f32_e32 v146, v123, v66
	s_waitcnt lgkmcnt(10)
	v_mfma_f32_32x32x16_bf16 v[66:81], v[162:165], v[130:133], v[50:65]
	v_cvt_pk_bf16_f32 v160, v118, v119
	v_cvt_pk_bf16_f32 v161, v120, v121
	ds_read_b64_tr_b16 v[118:119], v199 offset:25600
	ds_read_b64_tr_b16 v[120:121], v199 offset:26112
	s_waitcnt lgkmcnt(11)
	v_mfma_f32_32x32x16_bf16 v[82:97], v[166:169], v[134:137], v[82:97]
	v_add_f32_e32 v146, v124, v146
	v_add_f32_e32 v146, v125, v146
	v_add_f32_e32 v146, v126, v146
	v_add_f32_e32 v146, v127, v146
	v_cvt_pk_bf16_f32 v154, v122, v123
	v_cvt_pk_bf16_f32 v155, v124, v125
	ds_read_b64_tr_b16 v[122:123], v199 offset:29696
	ds_read_b64_tr_b16 v[124:125], v199 offset:30208
	s_waitcnt lgkmcnt(12)
	v_mfma_f32_32x32x16_bf16 v[66:81], v[170:173], v[134:137], v[66:81]
	v_add_f32_e32 v146, v128, v146
	v_add_f32_e32 v146, v129, v146
	v_add_f32_e32 v146, v98, v146
	v_add_f32_e32 v146, v99, v146
	v_cvt_pk_bf16_f32 v156, v126, v127
	v_cvt_pk_bf16_f32 v157, v128, v129
	ds_read_b64_tr_b16 v[126:127], v199 offset:26624
	ds_read_b64_tr_b16 v[128:129], v199 offset:27136
	s_waitcnt lgkmcnt(13)
	v_mfma_f32_32x32x16_bf16 v[82:97], v[174:177], v[138:141], v[82:97]
	v_add_f32_e32 v146, v100, v146
	v_add_f32_e32 v146, v101, v146
	v_add_f32_e32 v146, v102, v146
	v_add_f32_e32 v146, v103, v146
	v_cvt_pk_bf16_f32 v150, v98, v99
	v_cvt_pk_bf16_f32 v151, v100, v101
	ds_read_b64_tr_b16 v[98:99], v199 offset:30720
	ds_read_b64_tr_b16 v[100:101], v199 offset:31232
	s_waitcnt lgkmcnt(14)
	v_mfma_f32_32x32x16_bf16 v[66:81], v[178:181], v[138:141], v[66:81]
	v_add_f32_e32 v146, v104, v146
	v_add_f32_e32 v146, v105, v146
	v_add_f32_e32 v146, v106, v146
	v_add_f32_e32 v146, v107, v146
	v_cvt_pk_bf16_f32 v152, v102, v103
	v_cvt_pk_bf16_f32 v153, v104, v105
	ds_read_b64_tr_b16 v[102:103], v199 offset:27648
	ds_read_b64_tr_b16 v[104:105], v199 offset:28160
	s_waitcnt lgkmcnt(14)
	v_mfma_f32_32x32x16_bf16 v[82:97], v[182:185], v[142:145], v[82:97]
	v_add_f32_e32 v146, v108, v146
	v_add_f32_e32 v146, v109, v146
	v_add_f32_e32 v146, v110, v146
	v_add_f32_e32 v162, v111, v146
	v_cvt_pk_bf16_f32 v146, v106, v107
	v_cvt_pk_bf16_f32 v147, v108, v109
	ds_read_b64_tr_b16 v[106:107], v199 offset:31744
	ds_read_b64_tr_b16 v[108:109], v199 offset:32256
	v_mfma_f32_32x32x16_bf16 v[66:81], v[186:189], v[142:145], v[66:81]
	v_add_f32_e32 v148, v112, v162
	v_add_f32_e32 v148, v113, v148
	v_add_f32_e32 v199, 0, v148
	v_cvt_pk_bf16_f32 v148, v110, v111
	v_cvt_pk_bf16_f32 v149, v112, v113
	s_add_i32 s0, s89, s84
	s_mov_b32 s1, m0
	s_mov_b32 m0, s0
	s_nop 0
	global_load_lds_dwordx4 v[196:197], off
	s_mov_b32 m0, s1
	s_add_i32 s0, s87, s8
	s_mov_b32 s1, m0
	s_mov_b32 m0, s0
	s_nop 0
	global_load_lds_dwordx4 v[194:195], off
	s_mov_b32 m0, s1
	s_waitcnt lgkmcnt(14)
	v_mfma_f32_32x32x16_bf16 v[18:33], v[158:161], v[190:193], v[18:33]
	v_exp_f32_e32 v82, v82
	v_exp_f32_e32 v83, v83
	v_exp_f32_e32 v84, v84
	v_exp_f32_e32 v85, v85
	s_waitcnt lgkmcnt(12)
	v_mfma_f32_32x32x16_bf16 v[34:49], v[158:161], v[114:117], v[34:49]
	v_exp_f32_e32 v86, v86
	v_exp_f32_e32 v87, v87
	v_exp_f32_e32 v88, v88
	v_exp_f32_e32 v89, v89
	v_add_u32_e32 v110, s87, v232
	ds_read_b128 v[190:193], v110
	ds_read_b128 v[186:189], v110 offset:512
	s_waitcnt lgkmcnt(12)
	v_mfma_f32_32x32x16_bf16 v[18:33], v[154:157], v[118:121], v[18:33]
	v_exp_f32_e32 v90, v90
	v_exp_f32_e32 v91, v91
	v_exp_f32_e32 v92, v92
	v_exp_f32_e32 v93, v93
	ds_read_b128 v[182:185], v110 offset:2048
	ds_read_b128 v[178:181], v110 offset:2560
	s_waitcnt lgkmcnt(12)
	v_mfma_f32_32x32x16_bf16 v[34:49], v[154:157], v[122:125], v[34:49]
	v_exp_f32_e32 v94, v94
	v_exp_f32_e32 v95, v95
	v_exp_f32_e32 v96, v96
	v_exp_f32_e32 v97, v97
	ds_read_b128 v[174:177], v110 offset:4096
	ds_read_b128 v[170:173], v110 offset:4608
	s_waitcnt lgkmcnt(12)
	v_mfma_f32_32x32x16_bf16 v[18:33], v[150:153], v[126:129], v[18:33]
	v_exp_f32_e32 v66, v66
	v_exp_f32_e32 v67, v67
	v_exp_f32_e32 v68, v68
	v_exp_f32_e32 v69, v69
	ds_read_b128 v[166:169], v110 offset:6144
	ds_read_b128 v[162:165], v110 offset:6656
	s_waitcnt lgkmcnt(12)
	v_mfma_f32_32x32x16_bf16 v[34:49], v[150:153], v[98:101], v[34:49]
	v_exp_f32_e32 v70, v70
	v_exp_f32_e32 v71, v71
	v_exp_f32_e32 v72, v72
	v_exp_f32_e32 v73, v73
	s_waitcnt lgkmcnt(10)
	v_mfma_f32_32x32x16_bf16 v[18:33], v[146:149], v[102:105], v[18:33]
	v_exp_f32_e32 v74, v74
	v_exp_f32_e32 v75, v75
	v_exp_f32_e32 v76, v76
	v_exp_f32_e32 v77, v77
	s_waitcnt lgkmcnt(8)
	v_mfma_f32_32x32x16_bf16 v[34:49], v[146:149], v[106:109], v[34:49]
	v_exp_f32_e32 v78, v78
	v_exp_f32_e32 v79, v79
	v_exp_f32_e32 v80, v80
	v_exp_f32_e32 v81, v81
	s_add_i32 s0, s87, 0x2000
	s_cmpk_lg_i32 s87, 0x4000
	s_mov_b32 s36, s89
	s_cselect_b32 s89, s0, 0
	s_add_i32 s6, s6, 2
	s_add_i32 s38, s38, 2
	v_add_f32_e32 v102, v206, v198
	v_lshl_add_u64 v[194:195], v[194:195], 0, s[14:15]
	v_lshl_add_u64 v[196:197], v[196:197], 0, s[14:15]
	v_lshl_add_u64 v[100:101], v[226:227], 0, s[14:15]
	v_lshl_add_u64 v[98:99], v[228:229], 0, s[14:15]
	v_add_f32_e32 v206, v102, v199
	s_waitcnt vmcnt(2) lgkmcnt(0)
	s_barrier
	s_cmp_ge_u32 s6, s82
	s_cbranch_scc0 .LBB0_1097
	s_add_i32 s0, s6, -4
	s_cmp_ge_u32 s0, s82
	s_cbranch_scc1 .LBB0_1132
	s_add_i32 s90, s6, -5
